# out-proj GEMM: split-K factor of the tail tiles 8 -> 2
# baseline (speedup 1.0000x reference)
; DI int TID() { int t = threadIdx.x; asm volatile("" : "+v"(t)); return t; }
; DI int BID() { int t = blockIdx.x; asm volatile("" : "+s"(t)); return t; }
;   constexpr int BN = 128 * WM, GBUF = (256 + BN) * GSTR;
;   const int tid = TID(), lane = tid & 63, wv = tid >> 6, l31 = lane & 31, hh = lane >> 5;
;   const int wm = (WM == 1) ? wv : (wv & 3), wn = (WM == 1) ? 0 : (wv >> 2);
;   const int xcd = BID() & 7, slot = BID() >> 3, nslots = gridDim.x >> 3;
;   const int nk = K >> 6;
;   const int tiles_x = ((MT - xcd + 7) >> 3) * ntiles;
;   constexpr int NSP = NSPLIT > 0 ? NSPLIT : 1;
;   const int full = NSPLIT > 0 ? (tiles_x / nslots) * nslots : tiles_x;
;   const int nunits = full + (tiles_x - full) * NSP;
;   for (int u = slot; u < nunits; u += nslots) {
;     const bool part = u >= full;
;     const int q = part ? full + (u - full) / NSP : u, ks = part ? (u - full) % NSP : 0;
;     const int mtl = q / ntiles, nt = q - mtl * ntiles, mt = mtl * 8 + xcd;
;     if (skipctx && (mt % PT) == 0) continue;
;     const int kt0 = part ? (ks * nk) / NSP : 0, kt1 = part ? ((ks + 1) * nk) / NSP : nk;
;     const bf16_t* Ag = A + (size_t)mt * 256 * K;
;     const bf16_t* Wg = W + (size_t)nt * BN * K;
;     f32x16 acc[WM][4];
; #pragma unroll
;     for (int mi = 0; mi < WM; ++mi)
; #pragma unroll
;       for (int nb = 0; nb < 4; ++nb)
; #pragma unroll
;         for (int i = 0; i < 16; ++i) acc[mi][nb][i] = 0.f;
;     uint4 ra0, ra1, ra2, ra3, rw0, rw1, rw2, rw3;
;     rw2 = make_uint4(0, 0, 0, 0); rw3 = rw2;
;     const int grow = tid >> 3, gcol = (tid & 7) * 8;
;     const bf16_t* ap = Ag + (size_t)grow * K + gcol;
;     const bf16_t* wp = Wg + (size_t)grow * K + gcol;
;     const int lo = grow * GSTR + (tid & 7) * 16;
.LBB0_94:
	s_andn2_b64 vcc, exec, s[0:1]
	s_cbranch_vccnz .LBB0_133
	s_cmp_gt_i32 s9, 4
	s_mov_b64 s[0:1], -1
	s_cbranch_scc0 .LBB0_120
	s_waitcnt vmcnt(1)
	v_mov_b32_e32 v0, v167
	s_mov_b32 s0, s50
	s_and_b32 s3, s0, 7
	s_mov_b32 s0, s50
	s_ashr_i32 s45, s0, 3
	s_sub_i32 s0, 0x8b, s3
	s_lshr_b32 s0, s0, 1
	s_and_b32 s0, s0, 0x44
	v_readlane_b32 s1, v253, 59
	s_mul_hi_u32 s1, s0, s1
	v_readlane_b32 s24, v254, 7
	s_mul_i32 s1, s1, s24
	s_sub_i32 s1, s0, s1
	s_mov_b32 s28, s24
	s_sub_i32 s24, s1, s24
	s_cmp_ge_u32 s1, s28
	s_cselect_b32 s1, s24, s1
	s_sub_i32 s24, s1, s28
	s_cmp_ge_u32 s1, s28
	s_cselect_b32 s1, s24, s1
	s_sub_i32 s46, s0, s1
	s_lshl_b32 s0, s1, 1
	s_add_i32 s47, s46, s0
	s_movk_i32 s34, 0x2000
	s_cmp_ge_i32 s45, s47
	v_readlane_b32 s25, v254, 8
	s_cbranch_scc1 .LBB0_119
	v_readlane_b32 s0, v255, 2
	v_readlane_b32 s1, v255, 3
	s_add_u32 s48, s0, 0x2000
	s_addc_u32 s49, s1, 0
	s_cmp_eq_u32 s12, 1
	s_mov_b32 s0, 0xa00000
	s_cselect_b32 s0, s0, 0x600000
	s_cmp_lg_u32 s12, 0
	s_cselect_b32 s0, s0, 0x3a0000
	v_readlane_b32 s24, v252, 4
	v_ashrrev_i32_e32 v2, 3, v0
	v_readlane_b32 s25, v252, 5
	s_add_u32 s0, s24, s0
	v_ashrrev_i32_e32 v3, 31, v2
	s_addc_u32 s1, s25, 0
	v_lshlrev_b64 v[4:5], 11, v[2:3]
	v_lshl_add_u64 v[6:7], s[76:77], 0, v[4:5]
	v_lshlrev_b32_e32 v1, 4, v0
	v_lshl_add_u64 v[4:5], s[0:1], 0, v[4:5]
	s_movk_i32 s0, 0x90
	v_and_b32_e32 v140, 0x70, v1
	v_mul_lo_u32 v1, v2, s0
	v_add3_u32 v188, 0, v1, v140
	v_and_b32_e32 v1, 0xdf, v0
	v_ashrrev_i32_e32 v169, 8, v0
	v_and_b32_e32 v187, 31, v0
	v_mul_u32_u24_e32 v189, 0x90, v1
	v_lshrrev_b32_e32 v1, 1, v0
	v_and_b32_e32 v190, 16, v1
	v_lshl_or_b32 v1, v169, 7, v187
	v_and_b32_e32 v186, 0xc0, v0
	v_mul_lo_u32 v1, v1, s0
	v_lshlrev_b32_e32 v0, 7, v0
	s_movk_i32 s0, 0x1000
	s_waitcnt vmcnt(0)
	v_lshl_add_u64 v[162:163], v[6:7], 0, v[140:141]
	v_lshl_add_u64 v[164:165], v[4:5], 0, v[140:141]
	v_add_u32_e32 v191, 0x9000, v1
	v_and_or_b32 v168, v0, s0, v187
	s_branch .LBB0_99

; #define SSTOREG(buf_) do { char* b_ = (buf_) + lo; \
;       *(uint4*)(b_) = ra0; *(uint4*)(b_ + 64 * GSTR) = ra1; *(uint4*)(b_ + 128 * GSTR) = ra2; *(uint4*)(b_ + 192 * GSTR) = ra3; \
;       *(uint4*)(b_ + 256 * GSTR) = rw0; *(uint4*)(b_ + 320 * GSTR) = rw1; \
;       if (WM == 2) { *(uint4*)(b_ + 384 * GSTR) = rw2; *(uint4*)(b_ + 448 * GSTR) = rw3; } } while (0)
; #define SSTOREG(buf_) do { char* b_ = (buf_) + lo; \
;       *(uint4*)(b_) = ra0; *(uint4*)(b_ + 64 * GSTR) = ra1; *(uint4*)(b_ + 128 * GSTR) = ra2; *(uint4*)(b_ + 192 * GSTR) = ra3; \
;       *(uint4*)(b_ + 256 * GSTR) = rw0; *(uint4*)(b_ + 320 * GSTR) = rw1; \
;       if (WM == 2) { *(uint4*)(b_ + 384 * GSTR) = rw2; *(uint4*)(b_ + 448 * GSTR) = rw3; } } while (0)
;     ...
;   for (int u = slot; u < nunits; u += nslots) {
;     const bool part = u >= full;
;     const int q = part ? full + (u - full) / NSP : u, ks = part ? (u - full) % NSP : 0;
;     const int mtl = q / ntiles, nt = q - mtl * ntiles, mt = mtl * 8 + xcd;
;     if (skipctx && (mt % PT) == 0) continue;
;     const int kt0 = part ? (ks * nk) / NSP : 0, kt1 = part ? ((ks + 1) * nk) / NSP : nk;
;     const bf16_t* Ag = A + (size_t)mt * 256 * K;
;     const bf16_t* Wg = W + (size_t)nt * BN * K;
;     f32x16 acc[WM][4];
; #pragma unroll
;     for (int mi = 0; mi < WM; ++mi)
; #pragma unroll
;       for (int nb = 0; nb < 4; ++nb)
; #pragma unroll
;         for (int i = 0; i < 16; ++i) acc[mi][nb][i] = 0.f;
;     uint4 ra0, ra1, ra2, ra3, rw0, rw1, rw2, rw3;
;     rw2 = make_uint4(0, 0, 0, 0); rw3 = rw2;
;     const int grow = tid >> 3, gcol = (tid & 7) * 8;
;     const bf16_t* ap = Ag + (size_t)grow * K + gcol;
;     const bf16_t* wp = Wg + (size_t)grow * K + gcol;
;     const int lo = grow * GSTR + (tid & 7) * 16;
;     ...
;     GLOADG(kt0); SSTOREG(smem);
.LBB0_99:
	s_cmp_ge_i32 s45, s46
	s_cselect_b64 s[0:1], -1, 0
	s_sub_i32 s24, s45, s46
	s_lshr_b32 s25, s24, 1
	s_add_i32 s25, s25, s46
	s_cmp_lt_i32 s45, s46
	s_cselect_b64 s[30:31], -1, 0
	s_and_b64 s[28:29], s[30:31], exec
	s_cselect_b32 s25, s45, s25
	s_ashr_i32 s27, s25, 31
	s_lshr_b32 s27, s27, 30
	s_add_i32 s27, s25, s27
	s_ashr_i32 s27, s27, 2
	s_lshl_b32 s28, s27, 3
	s_or_b32 s28, s28, s3
	s_mul_hi_i32 s29, s28, 0x3e0f83e1
	s_lshr_b32 s36, s29, 31
	s_ashr_i32 s29, s29, 3
	s_add_i32 s29, s29, s36
	s_mul_i32 s29, s29, 33
	s_sub_i32 s29, s28, s29
	s_cmp_eq_u32 s29, 0
	s_cselect_b64 s[36:37], -1, 0
	s_and_b64 s[36:37], s[40:41], s[36:37]
	s_and_b64 vcc, exec, s[36:37]
	s_cbranch_vccnz .LBB0_98
	s_lshl_b32 s27, s27, 2
	s_and_b32 s24, s24, 1
	s_sub_i32 s38, s25, s27
	s_lshl_b32 s27, s24, 3
	s_lshl_b32 s24, s24, 4
	s_add_i32 s24, s24, 16
	s_lshr_b32 s36, s24, 1
	s_ashr_i32 s29, s28, 31
	s_ashr_i32 s39, s38, 31
	s_and_b64 s[24:25], s[30:31], exec
	s_cselect_b32 s27, 0, s27
	s_cselect_b32 s30, 16, s36
	s_lshl_b64 s[24:25], s[28:29], 19
	v_lshl_add_u64 v[170:171], v[162:163], 0, s[24:25]
	s_lshl_b64 s[24:25], s[38:39], 19
	v_lshl_add_u64 v[172:173], v[164:165], 0, s[24:25]
	s_mov_b64 s[24:25], 0x20000
	s_lshl_b32 s96, s27, 7
	v_lshl_add_u64 v[174:175], v[170:171], 0, s[24:25]
	s_waitcnt vmcnt(6)
	v_lshl_add_u64 v[180:181], v[172:173], 0, s[24:25]
	s_or_b32 s24, s27, 1
	s_mov_b64 s[36:37], 0x40000
	s_mov_b64 s[42:43], 0x60000
	s_cmp_lt_u32 s24, s30
	v_lshl_add_u64 v[176:177], v[170:171], 0, s[36:37]
	s_waitcnt vmcnt(4)
	v_lshl_add_u64 v[178:179], v[170:171], 0, s[42:43]
	v_lshl_add_u64 v[182:183], v[172:173], 0, s[36:37]
	v_lshl_add_u64 v[184:185], v[172:173], 0, s[42:43]
	s_cselect_b32 s24, s24, s27
	v_lshl_add_u64 v[0:1], v[170:171], 0, s[96:97]
	v_lshl_add_u64 v[4:5], v[174:175], 0, s[96:97]
	v_lshl_add_u64 v[8:9], v[176:177], 0, s[96:97]
	v_lshl_add_u64 v[12:13], v[178:179], 0, s[96:97]
	v_lshl_add_u64 v[16:17], v[172:173], 0, s[96:97]
	v_lshl_add_u64 v[20:21], v[180:181], 0, s[96:97]
	v_lshl_add_u64 v[24:25], v[182:183], 0, s[96:97]
	v_lshl_add_u64 v[28:29], v[184:185], 0, s[96:97]
	s_lshl_b32 s96, s24, 7
	v_lshl_add_u64 v[32:33], v[170:171], 0, s[96:97]
	global_load_dwordx4 v[0:3], v[0:1], off
	s_nop 0
	global_load_dwordx4 v[4:7], v[4:5], off
	s_nop 0
	global_load_dwordx4 v[8:11], v[8:9], off
	s_nop 0
	global_load_dwordx4 v[12:15], v[12:13], off
	s_nop 0
	global_load_dwordx4 v[16:19], v[16:17], off
	s_nop 0
	global_load_dwordx4 v[20:23], v[20:21], off
	s_nop 0
	global_load_dwordx4 v[24:27], v[24:25], off
	s_nop 0
	global_load_dwordx4 v[28:31], v[28:29], off
	v_lshl_add_u64 v[34:35], v[174:175], 0, s[96:97]
	v_lshl_add_u64 v[36:37], v[176:177], 0, s[96:97]
	v_lshl_add_u64 v[38:39], v[178:179], 0, s[96:97]
	v_lshl_add_u64 v[40:41], v[172:173], 0, s[96:97]
	v_lshl_add_u64 v[42:43], v[180:181], 0, s[96:97]
	v_lshl_add_u64 v[44:45], v[182:183], 0, s[96:97]
	v_lshl_add_u64 v[46:47], v[184:185], 0, s[96:97]
	global_load_dwordx4 v[158:161], v[32:33], off
	global_load_dwordx4 v[154:157], v[34:35], off
	global_load_dwordx4 v[150:153], v[36:37], off
	global_load_dwordx4 v[146:149], v[38:39], off
	global_load_dwordx4 v[142:145], v[40:41], off
	global_load_dwordx4 v[136:139], v[42:43], off
	global_load_dwordx4 v[132:135], v[44:45], off
	global_load_dwordx4 v[128:131], v[46:47], off
	v_mov_b32_e32 v127, 0
	s_mov_b64 s[16:17], 0x20000
	s_mov_b64 s[18:19], 0x40000
	s_mov_b64 s[10:11], 0x60000
	v_mov_b32_e32 v126, v127
	v_mov_b32_e32 v125, v127
	v_mov_b32_e32 v124, v127
	v_mov_b32_e32 v123, v127
	v_mov_b32_e32 v122, v127
	v_mov_b32_e32 v121, v127
	v_mov_b32_e32 v120, v127
	v_mov_b32_e32 v119, v127
	v_mov_b32_e32 v118, v127
	v_mov_b32_e32 v117, v127
	v_mov_b32_e32 v116, v127
	v_mov_b32_e32 v115, v127
	v_mov_b32_e32 v114, v127
	v_mov_b32_e32 v113, v127
	v_mov_b32_e32 v112, v127
	v_mov_b32_e32 v111, v127
	v_mov_b32_e32 v110, v127
	v_mov_b32_e32 v109, v127
	s_cmp_ge_u32 s27, s30
	v_mov_b32_e32 v108, v127
	v_mov_b32_e32 v107, v127
	v_mov_b32_e32 v106, v127
	s_waitcnt vmcnt(19)
	v_mov_b32_e32 v105, v127
	s_waitcnt vmcnt(18)
	v_mov_b32_e32 v104, v127
	s_waitcnt vmcnt(17)
	v_mov_b32_e32 v103, v127
	s_waitcnt vmcnt(16)
	v_mov_b32_e32 v102, v127
	v_mov_b32_e32 v101, v127
	v_mov_b32_e32 v100, v127
	v_mov_b32_e32 v99, v127
	v_mov_b32_e32 v98, v127
	v_mov_b32_e32 v97, v127
	v_mov_b32_e32 v96, v127
	v_mov_b32_e32 v95, v127
	v_mov_b32_e32 v94, v127
	v_mov_b32_e32 v93, v127
	s_waitcnt vmcnt(15)
	ds_write_b128 v188, v[0:3]
	s_waitcnt vmcnt(11)
	ds_write_b128 v188, v[16:19] offset:36864
	ds_write_b128 v188, v[4:7] offset:9216
	ds_write_b128 v188, v[8:11] offset:18432
	ds_write_b128 v188, v[12:15] offset:27648
	s_waitcnt vmcnt(10)
	ds_write_b128 v188, v[20:23] offset:46080
	s_waitcnt vmcnt(9)
	ds_write_b128 v188, v[24:27] offset:55296
	s_waitcnt vmcnt(8)
; #define SSTOREG(buf_) do { char* b_ = (buf_) + lo; \
;       *(uint4*)(b_) = ra0; *(uint4*)(b_ + 64 * GSTR) = ra1; *(uint4*)(b_ + 128 * GSTR) = ra2; *(uint4*)(b_ + 192 * GSTR) = ra3; \
;       *(uint4*)(b_ + 256 * GSTR) = rw0; *(uint4*)(b_ + 320 * GSTR) = rw1; \
;       if (WM == 2) { *(uint4*)(b_ + 384 * GSTR) = rw2; *(uint4*)(b_ + 448 * GSTR) = rw3; } } while (0)
; #define SSTOREG(buf_) do { char* b_ = (buf_) + lo; \
;       *(uint4*)(b_) = ra0; *(uint4*)(b_ + 64 * GSTR) = ra1; *(uint4*)(b_ + 128 * GSTR) = ra2; *(uint4*)(b_ + 192 * GSTR) = ra3; \
;       *(uint4*)(b_ + 256 * GSTR) = rw0; *(uint4*)(b_ + 320 * GSTR) = rw1; \
;       if (WM == 2) { *(uint4*)(b_ + 384 * GSTR) = rw2; *(uint4*)(b_ + 448 * GSTR) = rw3; } } while (0)
;     ...
;     f32x16 acc[WM][4];
; #pragma unroll
;     for (int mi = 0; mi < WM; ++mi)
; #pragma unroll
;       for (int nb = 0; nb < 4; ++nb)
; #pragma unroll
;         for (int i = 0; i < 16; ++i) acc[mi][nb][i] = 0.f;
;     uint4 ra0, ra1, ra2, ra3, rw0, rw1, rw2, rw3;
;     rw2 = make_uint4(0, 0, 0, 0); rw3 = rw2;
;     const int grow = tid >> 3, gcol = (tid & 7) * 8;
;     const bf16_t* ap = Ag + (size_t)grow * K + gcol;
;     const bf16_t* wp = Wg + (size_t)grow * K + gcol;
;     const int lo = grow * GSTR + (tid & 7) * 16;
;     ...
;     GLOADG(kt0); SSTOREG(smem);
;     if (WM == 2) GLOADG(kt0 + 1 < kt1 ? kt0 + 1 : kt0);
;     __syncthreads();
;     for (int kt = kt0; kt < kt1; ++kt) {
	ds_write_b128 v188, v[28:31] offset:64512
	v_mov_b32_e32 v92, v127
	v_mov_b32_e32 v91, v127
	v_mov_b32_e32 v90, v127
	v_mov_b32_e32 v89, v127
	v_mov_b32_e32 v88, v127
	v_mov_b32_e32 v87, v127
	v_mov_b32_e32 v86, v127
	v_mov_b32_e32 v85, v127
	v_mov_b32_e32 v84, v127
	v_mov_b32_e32 v83, v127
	v_mov_b32_e32 v82, v127
	v_mov_b32_e32 v81, v127
	v_mov_b32_e32 v80, v127
	v_mov_b32_e32 v79, v127
	v_mov_b32_e32 v78, v127
	v_mov_b32_e32 v77, v127
	v_mov_b32_e32 v76, v127
	v_mov_b32_e32 v75, v127
	v_mov_b32_e32 v74, v127
	v_mov_b32_e32 v73, v127
	v_mov_b32_e32 v72, v127
	v_mov_b32_e32 v71, v127
	v_mov_b32_e32 v70, v127
	v_mov_b32_e32 v69, v127
	v_mov_b32_e32 v68, v127
	v_mov_b32_e32 v67, v127
	v_mov_b32_e32 v66, v127
	v_mov_b32_e32 v65, v127
	v_mov_b32_e32 v64, v127
	v_mov_b32_e32 v63, v127
	v_mov_b32_e32 v62, v127
	v_mov_b32_e32 v61, v127
	v_mov_b32_e32 v60, v127
	v_mov_b32_e32 v59, v127
	v_mov_b32_e32 v58, v127
	v_mov_b32_e32 v57, v127
	v_mov_b32_e32 v56, v127
	v_mov_b32_e32 v55, v127
	v_mov_b32_e32 v54, v127
	v_mov_b32_e32 v53, v127
	v_mov_b32_e32 v52, v127
	v_mov_b32_e32 v51, v127
	v_mov_b32_e32 v50, v127
	v_mov_b32_e32 v49, v127
	v_mov_b32_e32 v48, v127
	v_mov_b32_e32 v47, v127
	v_mov_b32_e32 v46, v127
	v_mov_b32_e32 v45, v127
	v_mov_b32_e32 v44, v127
	v_mov_b32_e32 v43, v127
	v_mov_b32_e32 v42, v127
	v_mov_b32_e32 v41, v127
	v_mov_b32_e32 v40, v127
	v_mov_b32_e32 v39, v127
	v_mov_b32_e32 v38, v127
	v_mov_b32_e32 v37, v127
	v_mov_b32_e32 v36, v127
	v_mov_b32_e32 v35, v127
	v_mov_b32_e32 v34, v127
	v_mov_b32_e32 v33, v127
	v_mov_b32_e32 v32, v127
	v_mov_b32_e32 v31, v127
	v_mov_b32_e32 v30, v127
	v_mov_b32_e32 v29, v127
	v_mov_b32_e32 v28, v127
	v_mov_b32_e32 v27, v127
	v_mov_b32_e32 v26, v127
	v_mov_b32_e32 v25, v127
	v_mov_b32_e32 v24, v127
	v_mov_b32_e32 v23, v127
	v_mov_b32_e32 v22, v127
	v_mov_b32_e32 v21, v127
	v_mov_b32_e32 v20, v127
	v_mov_b32_e32 v19, v127
	v_mov_b32_e32 v18, v127
	v_mov_b32_e32 v17, v127
	v_mov_b32_e32 v16, v127
	v_mov_b32_e32 v15, v127
	v_mov_b32_e32 v14, v127
	v_mov_b32_e32 v13, v127
	v_mov_b32_e32 v12, v127
	v_mov_b32_e32 v11, v127
	v_mov_b32_e32 v10, v127
	v_mov_b32_e32 v9, v127
	v_mov_b32_e32 v8, v127
	v_mov_b32_e32 v7, v127
	v_mov_b32_e32 v6, v127
	v_mov_b32_e32 v5, v127
	v_mov_b32_e32 v4, v127
	v_mov_b32_e32 v3, v127
	v_mov_b32_e32 v2, v127
	v_mov_b32_e32 v1, v127
	v_mov_b32_e32 v0, v127
	s_waitcnt lgkmcnt(0)
	s_barrier
	s_cbranch_scc1 .LBB0_103
	v_mov_b32_e32 v0, 0
	v_mov_b32_e32 v1, v0
	v_mov_b32_e32 v2, v0
	v_mov_b32_e32 v3, v0
	v_mov_b32_e32 v4, v0
	v_mov_b32_e32 v5, v0
	v_mov_b32_e32 v6, v0
	v_mov_b32_e32 v7, v0
	v_mov_b32_e32 v8, v0
	v_mov_b32_e32 v9, v0
	v_mov_b32_e32 v10, v0
	v_mov_b32_e32 v11, v0
	v_mov_b32_e32 v12, v0
	v_mov_b32_e32 v13, v0
	v_mov_b32_e32 v14, v0
	v_mov_b32_e32 v15, v0
	v_mov_b32_e32 v16, v0
	v_mov_b32_e32 v17, v0
	v_mov_b32_e32 v18, v0
	v_mov_b32_e32 v19, v0
	v_mov_b32_e32 v20, v0
	v_mov_b32_e32 v21, v0
	v_mov_b32_e32 v22, v0
	v_mov_b32_e32 v23, v0
	v_mov_b32_e32 v24, v0
	v_mov_b32_e32 v25, v0
	v_mov_b32_e32 v26, v0
	v_mov_b32_e32 v27, v0
	v_mov_b32_e32 v28, v0
	v_mov_b32_e32 v29, v0
	v_mov_b32_e32 v30, v0
	v_mov_b32_e32 v31, v0
	v_mov_b32_e32 v32, v0
	v_mov_b32_e32 v33, v0
	v_mov_b32_e32 v34, v0
	v_mov_b32_e32 v35, v0
	v_mov_b32_e32 v36, v0
	v_mov_b32_e32 v37, v0
	v_mov_b32_e32 v38, v0
	v_mov_b32_e32 v39, v0
	v_mov_b32_e32 v40, v0
	v_mov_b32_e32 v41, v0
	v_mov_b32_e32 v42, v0
	v_mov_b32_e32 v43, v0
	v_mov_b32_e32 v44, v0
	v_mov_b32_e32 v45, v0
	v_mov_b32_e32 v46, v0
	v_mov_b32_e32 v47, v0
	v_mov_b32_e32 v48, v0
	v_mov_b32_e32 v49, v0
	v_mov_b32_e32 v50, v0
	v_mov_b32_e32 v51, v0
	v_mov_b32_e32 v52, v0
	v_mov_b32_e32 v53, v0
	v_mov_b32_e32 v54, v0
	v_mov_b32_e32 v55, v0
	v_mov_b32_e32 v56, v0
	v_mov_b32_e32 v57, v0
	v_mov_b32_e32 v58, v0
	v_mov_b32_e32 v59, v0
	v_mov_b32_e32 v60, v0
	v_mov_b32_e32 v61, v0
	v_mov_b32_e32 v62, v0
	v_mov_b32_e32 v63, v0
	v_mov_b32_e32 v64, v0
	v_mov_b32_e32 v65, v0
	v_mov_b32_e32 v66, v0
	v_mov_b32_e32 v67, v0
	v_mov_b32_e32 v68, v0
	v_mov_b32_e32 v69, v0
	v_mov_b32_e32 v70, v0
	v_mov_b32_e32 v71, v0
	v_mov_b32_e32 v72, v0
	v_mov_b32_e32 v73, v0
	v_mov_b32_e32 v74, v0
	v_mov_b32_e32 v75, v0
	v_mov_b32_e32 v76, v0
	v_mov_b32_e32 v77, v0
	v_mov_b32_e32 v78, v0
	v_mov_b32_e32 v79, v0
	v_mov_b32_e32 v80, v0
	v_mov_b32_e32 v81, v0
	v_mov_b32_e32 v82, v0
	v_mov_b32_e32 v83, v0
	v_mov_b32_e32 v84, v0
	v_mov_b32_e32 v85, v0
	v_mov_b32_e32 v86, v0
	v_mov_b32_e32 v87, v0
	v_mov_b32_e32 v88, v0
	v_mov_b32_e32 v89, v0
	v_mov_b32_e32 v90, v0
	v_mov_b32_e32 v91, v0
	v_mov_b32_e32 v92, v0
	v_mov_b32_e32 v93, v0
	v_mov_b32_e32 v94, v0
	v_mov_b32_e32 v95, v0
	v_mov_b32_e32 v96, v0
	v_mov_b32_e32 v97, v0
	v_mov_b32_e32 v98, v0
	v_mov_b32_e32 v99, v0
	v_mov_b32_e32 v100, v0
	v_mov_b32_e32 v101, v0
	v_mov_b32_e32 v102, v0
	v_mov_b32_e32 v103, v0
	v_mov_b32_e32 v104, v0
	v_mov_b32_e32 v105, v0
	v_mov_b32_e32 v106, v0
	v_mov_b32_e32 v107, v0
	v_mov_b32_e32 v108, v0
	v_mov_b32_e32 v109, v0
	v_mov_b32_e32 v110, v0
	v_mov_b32_e32 v111, v0
	v_mov_b32_e32 v112, v0
	v_mov_b32_e32 v113, v0
	v_mov_b32_e32 v114, v0
	v_mov_b32_e32 v115, v0
	v_mov_b32_e32 v116, v0
	v_mov_b32_e32 v117, v0
	v_mov_b32_e32 v118, v0
	v_mov_b32_e32 v119, v0
	v_mov_b32_e32 v120, v0
	v_mov_b32_e32 v121, v0
	v_mov_b32_e32 v122, v0
	v_mov_b32_e32 v123, v0
	v_mov_b32_e32 v124, v0
	v_mov_b32_e32 v125, v0
	v_mov_b32_e32 v126, v0
	v_mov_b32_e32 v127, v0
